# v82 + attention: next K/V tile written to the other LDS buffer between softmax and PV of the current tile, inter-tile section reduced to lgkmcnt(0) + barrier
# baseline (speedup 1.0000x reference)
.LBB0_336:
	s_add_i32 s17, s72, 1
	s_cmp_lg_u32 s72, 0
	s_cbranch_scc1 .Ladw_top
	s_waitcnt vmcnt(0)
	ds_write_b128 v193, v[164:167]
	ds_write_b128 v193, v[160:163] offset:9216
.Ladw_top:
	s_cmp_ge_u32 s17, s11
	s_waitcnt lgkmcnt(0)
	s_barrier
	s_cbranch_scc1 .LBB0_342
	s_cmp_gt_u32 s72, 2
	s_mov_b64 s[70:71], -1
	s_cbranch_scc0 .LBB0_339
	s_add_i32 s0, s16, s12
	s_ashr_i32 s1, s0, 31
	s_add_u32 s0, s13, s0
	s_addc_u32 s1, s14, s1
	s_mov_b64 s[70:71], 0

.LBB0_349:
	v_exp_f32_e32 v198, v112
	v_exp_f32_e32 v199, v80
	v_exp_f32_e32 v202, v113
	v_exp_f32_e32 v203, v81
	v_exp_f32_e32 v204, v114
	v_exp_f32_e32 v205, v82
	v_exp_f32_e32 v206, v115
	v_exp_f32_e32 v207, v83
	v_exp_f32_e32 v208, v116
	v_exp_f32_e32 v209, v84
	v_exp_f32_e32 v211, v85
	v_pk_add_f32 v[84:85], v[198:199], 0 op_sel_hi:[1,0]
	v_exp_f32_e32 v210, v117
	v_pk_add_f32 v[84:85], v[202:203], v[84:85]
	v_exp_f32_e32 v212, v118
	v_exp_f32_e32 v213, v86
	v_pk_add_f32 v[84:85], v[204:205], v[84:85]
	v_exp_f32_e32 v214, v119
	v_exp_f32_e32 v215, v87
	v_pk_add_f32 v[84:85], v[206:207], v[84:85]
	v_exp_f32_e32 v120, v120
	v_exp_f32_e32 v216, v121
	v_exp_f32_e32 v121, v88
	v_pk_add_f32 v[84:85], v[208:209], v[84:85]
	v_exp_f32_e32 v217, v89
	v_pk_add_f32 v[84:85], v[210:211], v[84:85]
	v_exp_f32_e32 v122, v122
	v_exp_f32_e32 v218, v123
	v_exp_f32_e32 v123, v90
	v_pk_add_f32 v[84:85], v[212:213], v[84:85]
	v_exp_f32_e32 v219, v91
	v_pk_add_f32 v[84:85], v[214:215], v[84:85]
	v_exp_f32_e32 v124, v124
	v_exp_f32_e32 v220, v125
	v_pk_add_f32 v[84:85], v[120:121], v[84:85]
	v_exp_f32_e32 v125, v92
	v_pk_add_f32 v[84:85], v[216:217], v[84:85]
	v_exp_f32_e32 v221, v93
	v_exp_f32_e32 v126, v126
	v_exp_f32_e32 v222, v127
	v_pk_add_f32 v[88:89], v[122:123], v[84:85]
	v_exp_f32_e32 v127, v94
	v_exp_f32_e32 v223, v95
	v_exp_f32_e32 v225, v64
	v_exp_f32_e32 v227, v65
	v_pk_add_f32 v[64:65], v[218:219], v[88:89]
	v_exp_f32_e32 v224, v96
	v_pk_add_f32 v[64:65], v[124:125], v[64:65]
	v_exp_f32_e32 v226, v97
	v_pk_add_f32 v[64:65], v[220:221], v[64:65]
	v_exp_f32_e32 v228, v98
	v_exp_f32_e32 v229, v66
	v_pk_add_f32 v[64:65], v[126:127], v[64:65]
	v_exp_f32_e32 v230, v99
	v_exp_f32_e32 v231, v67
	v_pk_add_f32 v[64:65], v[222:223], v[64:65]
	v_exp_f32_e32 v232, v100
	v_exp_f32_e32 v233, v68
	v_pk_add_f32 v[64:65], v[224:225], v[64:65]
	v_exp_f32_e32 v234, v101
	v_exp_f32_e32 v235, v69
	v_pk_add_f32 v[64:65], v[226:227], v[64:65]
	v_exp_f32_e32 v236, v102
	v_pk_add_f32 v[64:65], v[228:229], v[64:65]
	v_exp_f32_e32 v237, v70
	v_exp_f32_e32 v238, v103
	v_pk_add_f32 v[64:65], v[230:231], v[64:65]
	v_exp_f32_e32 v239, v71
	v_exp_f32_e32 v104, v104
	v_exp_f32_e32 v240, v105
	v_pk_add_f32 v[64:65], v[232:233], v[64:65]
	v_exp_f32_e32 v105, v72
	v_pk_add_f32 v[68:69], v[234:235], v[64:65]
	v_exp_f32_e32 v241, v73
	v_exp_f32_e32 v106, v106
	v_exp_f32_e32 v242, v107
	v_exp_f32_e32 v107, v74
	v_pk_add_f32 v[68:69], v[236:237], v[68:69]
	v_exp_f32_e32 v243, v75
	v_pk_add_f32 v[68:69], v[238:239], v[68:69]
	v_exp_f32_e32 v108, v108
	v_exp_f32_e32 v244, v109
	v_exp_f32_e32 v109, v76
	v_pk_add_f32 v[68:69], v[104:105], v[68:69]
	v_exp_f32_e32 v245, v77
	v_pk_add_f32 v[68:69], v[240:241], v[68:69]
	v_exp_f32_e32 v110, v110
	v_exp_f32_e32 v246, v111
	v_exp_f32_e32 v111, v78
	v_pk_add_f32 v[68:69], v[106:107], v[68:69]
	v_exp_f32_e32 v247, v79
	v_pk_add_f32 v[68:69], v[242:243], v[68:69]
	v_cvt_pk_bf16_f32 v116, v198, v202
	v_cvt_pk_bf16_f32 v117, v204, v206
	v_cvt_pk_bf16_f32 v118, v208, v210
	v_cvt_pk_bf16_f32 v119, v212, v214
	v_cvt_pk_bf16_f32 v112, v120, v216
	s_nop 0
	v_pk_add_f32 v[68:69], v[108:109], v[68:69]
	v_cvt_pk_bf16_f32 v113, v122, v218
	v_cvt_pk_bf16_f32 v114, v124, v220
	v_cvt_pk_bf16_f32 v115, v126, v222
	v_cvt_pk_bf16_f32 v100, v224, v226
	v_cvt_pk_bf16_f32 v101, v228, v230
	s_nop 0
	v_pk_add_f32 v[68:69], v[244:245], v[68:69]
	v_cvt_pk_bf16_f32 v102, v232, v234
	v_cvt_pk_bf16_f32 v103, v236, v238
	v_cvt_pk_bf16_f32 v96, v104, v240
	v_cvt_pk_bf16_f32 v97, v106, v242
	v_cvt_pk_bf16_f32 v98, v108, v244
	s_nop 0
	v_pk_add_f32 v[68:69], v[110:111], v[68:69]
	v_cvt_pk_bf16_f32 v99, v110, v246
	v_cvt_pk_bf16_f32 v80, v199, v203
	v_cvt_pk_bf16_f32 v81, v205, v207
	v_cvt_pk_bf16_f32 v82, v209, v211
	v_cvt_pk_bf16_f32 v83, v213, v215
	s_nop 0
	v_pk_add_f32 v[72:73], v[246:247], v[68:69]
	v_cvt_pk_bf16_f32 v84, v121, v217
	v_cvt_pk_bf16_f32 v85, v123, v219
	v_cvt_pk_bf16_f32 v86, v125, v221
	v_cvt_pk_bf16_f32 v87, v127, v223
	v_cvt_pk_bf16_f32 v64, v225, v227
	s_nop 0
	v_pk_add_f32 v[190:191], v[190:191], v[72:73]
	v_cvt_pk_bf16_f32 v65, v229, v231
	v_cvt_pk_bf16_f32 v66, v233, v235
	v_cvt_pk_bf16_f32 v67, v237, v239
	v_cvt_pk_bf16_f32 v68, v105, v241
	v_cvt_pk_bf16_f32 v69, v107, v243
	v_cvt_pk_bf16_f32 v70, v109, v245
	v_cvt_pk_bf16_f32 v71, v111, v247
	s_cmp_ge_u32 s17, s11
	s_cbranch_scc1 .Ladw_nst
	v_xor_b32_e32 v198, 0x8000, v193
	s_waitcnt vmcnt(0)
	ds_write_b128 v198, v[164:167]
	ds_write_b128 v198, v[160:163] offset:9216
.Ladw_nst:
	ds_read_b64_tr_b16 v[72:73], v195 offset:9216
	ds_read_b64_tr_b16 v[74:75], v195 offset:10368
	s_waitcnt lgkmcnt(0)
	v_mfma_f32_32x32x16_bf16 v[48:63], v[72:75], v[116:119], v[48:63]
	v_mfma_f32_32x32x16_bf16 v[16:31], v[72:75], v[80:83], v[16:31]
	ds_read_b64_tr_b16 v[72:73], v195 offset:9280
	ds_read_b64_tr_b16 v[74:75], v195 offset:10432
	s_waitcnt lgkmcnt(0)
	v_mfma_f32_32x32x16_bf16 v[32:47], v[72:75], v[116:119], v[32:47]
	v_mfma_f32_32x32x16_bf16 v[0:15], v[72:75], v[80:83], v[0:15]
	ds_read_b64_tr_b16 v[72:73], v195 offset:11520
	ds_read_b64_tr_b16 v[74:75], v195 offset:12672
	s_waitcnt lgkmcnt(0)
	v_mfma_f32_32x32x16_bf16 v[48:63], v[72:75], v[112:115], v[48:63]
	v_mfma_f32_32x32x16_bf16 v[16:31], v[72:75], v[84:87], v[16:31]
	ds_read_b64_tr_b16 v[72:73], v195 offset:11584
	ds_read_b64_tr_b16 v[74:75], v195 offset:12736
	s_waitcnt lgkmcnt(0)
	v_mfma_f32_32x32x16_bf16 v[32:47], v[72:75], v[112:115], v[32:47]
	v_mfma_f32_32x32x16_bf16 v[0:15], v[72:75], v[84:87], v[0:15]
	ds_read_b64_tr_b16 v[72:73], v195 offset:13824
	ds_read_b64_tr_b16 v[74:75], v195 offset:14976
	s_waitcnt lgkmcnt(0)
	v_mfma_f32_32x32x16_bf16 v[48:63], v[72:75], v[100:103], v[48:63]
	v_mfma_f32_32x32x16_bf16 v[16:31], v[72:75], v[64:67], v[16:31]
	ds_read_b64_tr_b16 v[72:73], v195 offset:13888
	ds_read_b64_tr_b16 v[74:75], v195 offset:15040
	s_waitcnt lgkmcnt(0)
	v_mfma_f32_32x32x16_bf16 v[0:15], v[72:75], v[64:67], v[0:15]
	ds_read_b64_tr_b16 v[64:65], v195 offset:16128
	ds_read_b64_tr_b16 v[66:67], v195 offset:17280
	v_mfma_f32_32x32x16_bf16 v[32:47], v[72:75], v[100:103], v[32:47]
	s_waitcnt lgkmcnt(0)
	v_mfma_f32_32x32x16_bf16 v[48:63], v[64:67], v[96:99], v[48:63]
	v_mfma_f32_32x32x16_bf16 v[16:31], v[64:67], v[68:71], v[16:31]
	ds_read_b64_tr_b16 v[64:65], v195 offset:16192
	ds_read_b64_tr_b16 v[66:67], v195 offset:17344
	s_waitcnt lgkmcnt(0)
	v_mfma_f32_32x32x16_bf16 v[32:47], v[64:67], v[96:99], v[32:47]
	v_mfma_f32_32x32x16_bf16 v[0:15], v[64:67], v[68:71], v[0:15]
	s_branch .LBB0_350
.Ladw_skip:
	s_cmp_ge_u32 s17, s11
	s_cbranch_scc1 .Ladw_nss
	v_xor_b32_e32 v198, 0x8000, v193
	s_waitcnt vmcnt(0)
	ds_write_b128 v198, v[164:167]
	ds_write_b128 v198, v[160:163] offset:9216
.Ladw_nss:
.LBB0_350:
	v_xor_b32_e32 v193, 0x8000, v193
	v_xor_b32_e32 v194, 0x8000, v194
	v_xor_b32_e32 v195, 0x8000, v195
	s_add_i32 s12, s12, 64
	s_cmp_eq_u32 s11, s17
	s_cbranch_scc1 .LBB0_330
	s_mov_b32 s72, s17
	s_branch .LBB0_336
